# GEMM main loops: loop-end scalars moved before the last barrier (back-edge rotation) and LDS fragment reads issued first in every load segment
# baseline (speedup 1.0000x reference)
.LBB0_264:
	ds_read_b128 v[210:213], v160
	ds_read_b128 v[214:217], v160 offset:1024
	ds_read_b128 v[218:221], v160 offset:2048
	ds_read_b128 v[222:225], v160 offset:3072
	ds_read_b128 v[226:229], v160 offset:4096
	ds_read_b128 v[230:233], v160 offset:5120
	ds_read_b128 v[234:237], v160 offset:6144
	ds_read_b128 v[238:241], v160 offset:7168
	s_add_i32 s22, s84, 2
	s_add_u32 s0, s82, 0x80
	s_addc_u32 s1, s83, 0
	s_add_i32 s30, 0, 0x10000
	s_cmp_eq_u32 s57, s84
	s_cselect_b32 s85, s45, s1
	s_cselect_b32 s84, s44, s0
	v_add_u32_e32 v154, s30, v139
	s_cselect_b32 s1, s81, vcc_hi
	s_cselect_b32 s0, s80, vcc_lo
	s_add_i32 s86, 0, 0x14000
	ds_read_b128 v[130:133], v154
	ds_read_b128 v[150:153], v154 offset:1024
	ds_read_b128 v[162:165], v154 offset:2048
	ds_read_b128 v[166:169], v154 offset:3072
	v_add_u32_e32 v154, s86, v139
	ds_read_b128 v[194:197], v154
	ds_read_b128 v[198:201], v154 offset:1024
	ds_read_b128 v[202:205], v154 offset:2048
	ds_read_b128 v[206:209], v154 offset:3072
	v_lshl_add_u64 v[154:155], s[82:83], 0, v[146:147]
	s_add_i32 m0, s91, 0xc000
	global_load_lds_dwordx4 v[154:155], off
	v_lshl_add_u64 v[154:155], s[82:83], 0, v[148:149]
	s_add_i32 m0, s91, 0xe000
	s_nop 0
	global_load_lds_dwordx4 v[154:155], off
	s_waitcnt vmcnt(8)
	s_waitcnt lgkmcnt(0)
	s_barrier
	s_waitcnt lgkmcnt(0)
	v_mfma_f32_16x16x32_bf16 v[126:129], v[130:133], v[210:213], v[126:129]
	v_mfma_f32_16x16x32_bf16 v[122:125], v[162:165], v[210:213], v[122:125]
	v_mfma_f32_16x16x32_bf16 v[110:113], v[130:133], v[218:221], v[110:113]
	v_mfma_f32_16x16x32_bf16 v[106:109], v[162:165], v[218:221], v[106:109]
	v_mfma_f32_16x16x32_bf16 v[94:97], v[130:133], v[226:229], v[94:97]
	v_mfma_f32_16x16x32_bf16 v[90:93], v[162:165], v[226:229], v[90:93]
	v_mfma_f32_16x16x32_bf16 v[78:81], v[130:133], v[234:237], v[78:81]
	v_mfma_f32_16x16x32_bf16 v[74:77], v[162:165], v[234:237], v[74:77]
	v_mfma_f32_16x16x32_bf16 v[126:129], v[150:153], v[214:217], v[126:129]
	v_mfma_f32_16x16x32_bf16 v[122:125], v[166:169], v[214:217], v[122:125]
	v_mfma_f32_16x16x32_bf16 v[110:113], v[150:153], v[222:225], v[110:113]
	v_mfma_f32_16x16x32_bf16 v[106:109], v[166:169], v[222:225], v[106:109]
	v_mfma_f32_16x16x32_bf16 v[94:97], v[150:153], v[230:233], v[94:97]
	v_mfma_f32_16x16x32_bf16 v[90:93], v[166:169], v[230:233], v[90:93]
	v_mfma_f32_16x16x32_bf16 v[78:81], v[150:153], v[238:241], v[78:81]
	v_mfma_f32_16x16x32_bf16 v[74:77], v[166:169], v[238:241], v[74:77]
	v_mfma_f32_16x16x32_bf16 v[118:121], v[194:197], v[210:213], v[118:121]
	v_mfma_f32_16x16x32_bf16 v[114:117], v[202:205], v[210:213], v[114:117]
	v_mfma_f32_16x16x32_bf16 v[102:105], v[194:197], v[218:221], v[102:105]
	v_mfma_f32_16x16x32_bf16 v[98:101], v[202:205], v[218:221], v[98:101]
	v_mfma_f32_16x16x32_bf16 v[86:89], v[194:197], v[226:229], v[86:89]
	v_mfma_f32_16x16x32_bf16 v[82:85], v[202:205], v[226:229], v[82:85]
	v_mfma_f32_16x16x32_bf16 v[70:73], v[194:197], v[234:237], v[70:73]
	v_mfma_f32_16x16x32_bf16 v[66:69], v[202:205], v[234:237], v[66:69]
	v_mfma_f32_16x16x32_bf16 v[118:121], v[198:201], v[214:217], v[118:121]
	v_mfma_f32_16x16x32_bf16 v[114:117], v[206:209], v[214:217], v[114:117]
	v_mfma_f32_16x16x32_bf16 v[102:105], v[198:201], v[222:225], v[102:105]
	v_mfma_f32_16x16x32_bf16 v[98:101], v[206:209], v[222:225], v[98:101]
	v_mfma_f32_16x16x32_bf16 v[86:89], v[198:201], v[230:233], v[86:89]
	v_mfma_f32_16x16x32_bf16 v[82:85], v[206:209], v[230:233], v[82:85]
	v_mfma_f32_16x16x32_bf16 v[70:73], v[198:201], v[238:241], v[70:73]
	v_mfma_f32_16x16x32_bf16 v[66:69], v[206:209], v[238:241], v[66:69]
	s_barrier
	ds_read_b128 v[210:213], v160 offset:16384
	ds_read_b128 v[214:217], v160 offset:17408
	ds_read_b128 v[218:221], v160 offset:18432
	ds_read_b128 v[222:225], v160 offset:19456
	ds_read_b128 v[226:229], v160 offset:20480
	ds_read_b128 v[230:233], v160 offset:21504
	ds_read_b128 v[234:237], v160 offset:22528
	ds_read_b128 v[238:241], v160 offset:23552
	s_add_i32 s30, s30, s99
	v_lshl_add_u64 v[154:155], s[0:1], 0, v[32:33]
	s_mov_b32 m0, s30
	global_load_lds_dwordx4 v[154:155], off
	s_add_i32 m0, s30, 0x2000
	v_lshl_add_u64 v[158:159], s[0:1], 0, v[144:145]
	s_add_u32 s0, s0, s66
	s_addc_u32 s1, s1, s67
	s_add_i32 s30, s86, s99
	global_load_lds_dwordx4 v[158:159], off
	v_lshl_add_u64 v[242:243], s[0:1], 0, v[32:33]
	s_mov_b32 m0, s30
	v_lshl_add_u64 v[244:245], s[0:1], 0, v[144:145]
	global_load_lds_dwordx4 v[242:243], off
	s_add_i32 m0, s30, 0x2000
	v_lshl_add_u64 v[246:247], s[84:85], 0, v[140:141]
	global_load_lds_dwordx4 v[244:245], off
	s_mov_b32 m0, s91
	v_lshl_add_u64 v[248:249], s[84:85], 0, v[142:143]
	global_load_lds_dwordx4 v[246:247], off
	s_mov_b32 m0, s20
	s_nop 0
	global_load_lds_dwordx4 v[248:249], off
	s_waitcnt vmcnt(8)
	s_waitcnt lgkmcnt(0)
	s_barrier
	s_waitcnt lgkmcnt(0)
	v_mfma_f32_16x16x32_bf16 v[62:65], v[130:133], v[210:213], v[62:65]
	v_mfma_f32_16x16x32_bf16 v[58:61], v[162:165], v[210:213], v[58:61]
	v_mfma_f32_16x16x32_bf16 v[46:49], v[130:133], v[218:221], v[46:49]
	v_mfma_f32_16x16x32_bf16 v[42:45], v[162:165], v[218:221], v[42:45]
	v_mfma_f32_16x16x32_bf16 v[28:31], v[130:133], v[226:229], v[28:31]
	v_mfma_f32_16x16x32_bf16 v[24:27], v[162:165], v[226:229], v[24:27]
	v_mfma_f32_16x16x32_bf16 v[12:15], v[130:133], v[234:237], v[12:15]
	v_mfma_f32_16x16x32_bf16 v[8:11], v[162:165], v[234:237], v[8:11]
	v_mfma_f32_16x16x32_bf16 v[62:65], v[150:153], v[214:217], v[62:65]
	v_mfma_f32_16x16x32_bf16 v[58:61], v[166:169], v[214:217], v[58:61]
	v_mfma_f32_16x16x32_bf16 v[46:49], v[150:153], v[222:225], v[46:49]
	v_mfma_f32_16x16x32_bf16 v[42:45], v[166:169], v[222:225], v[42:45]
	v_mfma_f32_16x16x32_bf16 v[28:31], v[150:153], v[230:233], v[28:31]
	v_mfma_f32_16x16x32_bf16 v[24:27], v[166:169], v[230:233], v[24:27]
	v_mfma_f32_16x16x32_bf16 v[12:15], v[150:153], v[238:241], v[12:15]
	v_mfma_f32_16x16x32_bf16 v[8:11], v[166:169], v[238:241], v[8:11]
	v_mfma_f32_16x16x32_bf16 v[54:57], v[194:197], v[210:213], v[54:57]
	v_mfma_f32_16x16x32_bf16 v[50:53], v[202:205], v[210:213], v[50:53]
	v_mfma_f32_16x16x32_bf16 v[38:41], v[194:197], v[218:221], v[38:41]
	v_mfma_f32_16x16x32_bf16 v[34:37], v[202:205], v[218:221], v[34:37]
	v_mfma_f32_16x16x32_bf16 v[20:23], v[194:197], v[226:229], v[20:23]
	v_mfma_f32_16x16x32_bf16 v[16:19], v[202:205], v[226:229], v[16:19]
	v_mfma_f32_16x16x32_bf16 v[4:7], v[194:197], v[234:237], v[4:7]
	v_mfma_f32_16x16x32_bf16 v[0:3], v[202:205], v[234:237], v[0:3]
	v_mfma_f32_16x16x32_bf16 v[54:57], v[198:201], v[214:217], v[54:57]
	v_mfma_f32_16x16x32_bf16 v[50:53], v[206:209], v[214:217], v[50:53]
	v_mfma_f32_16x16x32_bf16 v[38:41], v[198:201], v[222:225], v[38:41]
	v_mfma_f32_16x16x32_bf16 v[34:37], v[206:209], v[222:225], v[34:37]
	v_mfma_f32_16x16x32_bf16 v[20:23], v[198:201], v[230:233], v[20:23]
	v_mfma_f32_16x16x32_bf16 v[16:19], v[206:209], v[230:233], v[16:19]
	v_mfma_f32_16x16x32_bf16 v[4:7], v[198:201], v[238:241], v[4:7]
	v_mfma_f32_16x16x32_bf16 v[0:3], v[206:209], v[238:241], v[0:3]
	s_barrier
	ds_read_b128 v[210:213], v160 offset:32768
	ds_read_b128 v[214:217], v160 offset:33792
	ds_read_b128 v[218:221], v160 offset:34816
	ds_read_b128 v[222:225], v160 offset:35840
	ds_read_b128 v[226:229], v160 offset:36864
	ds_read_b128 v[230:233], v160 offset:37888
	ds_read_b128 v[234:237], v160 offset:38912
	ds_read_b128 v[238:241], v160 offset:39936
	s_add_i32 s30, 0, 0x18000
	v_add_u32_e32 v156, s30, v139
	s_add_i32 s86, 0, 0x1c000
	ds_read_b128 v[130:133], v156
	ds_read_b128 v[150:153], v156 offset:1024
	ds_read_b128 v[162:165], v156 offset:2048
	ds_read_b128 v[166:169], v156 offset:3072
	v_add_u32_e32 v156, s86, v139
	ds_read_b128 v[194:197], v156
	ds_read_b128 v[198:201], v156 offset:1024
	ds_read_b128 v[202:205], v156 offset:2048
	ds_read_b128 v[206:209], v156 offset:3072
	s_add_u32 s0, s84, s66
	s_addc_u32 s1, s85, s67
	s_mov_b32 m0, s25
	v_lshl_add_u64 v[250:251], s[0:1], 0, v[140:141]
	global_load_lds_dwordx4 v[250:251], off
	v_lshl_add_u64 v[250:251], s[0:1], 0, v[142:143]
	s_mov_b32 m0, s52
	s_nop 0
	global_load_lds_dwordx4 v[250:251], off
	s_waitcnt vmcnt(8)
	s_waitcnt lgkmcnt(0)
	s_barrier
	s_waitcnt lgkmcnt(0)
	v_mfma_f32_16x16x32_bf16 v[126:129], v[130:133], v[210:213], v[126:129]
	v_mfma_f32_16x16x32_bf16 v[122:125], v[162:165], v[210:213], v[122:125]
	v_mfma_f32_16x16x32_bf16 v[110:113], v[130:133], v[218:221], v[110:113]
	v_mfma_f32_16x16x32_bf16 v[106:109], v[162:165], v[218:221], v[106:109]
	v_mfma_f32_16x16x32_bf16 v[94:97], v[130:133], v[226:229], v[94:97]
	v_mfma_f32_16x16x32_bf16 v[90:93], v[162:165], v[226:229], v[90:93]
	v_mfma_f32_16x16x32_bf16 v[78:81], v[130:133], v[234:237], v[78:81]
	v_mfma_f32_16x16x32_bf16 v[74:77], v[162:165], v[234:237], v[74:77]
	v_mfma_f32_16x16x32_bf16 v[126:129], v[150:153], v[214:217], v[126:129]
	v_mfma_f32_16x16x32_bf16 v[122:125], v[166:169], v[214:217], v[122:125]
	v_mfma_f32_16x16x32_bf16 v[110:113], v[150:153], v[222:225], v[110:113]
	v_mfma_f32_16x16x32_bf16 v[106:109], v[166:169], v[222:225], v[106:109]
	v_mfma_f32_16x16x32_bf16 v[94:97], v[150:153], v[230:233], v[94:97]
	v_mfma_f32_16x16x32_bf16 v[90:93], v[166:169], v[230:233], v[90:93]
	v_mfma_f32_16x16x32_bf16 v[78:81], v[150:153], v[238:241], v[78:81]
	v_mfma_f32_16x16x32_bf16 v[74:77], v[166:169], v[238:241], v[74:77]
	v_mfma_f32_16x16x32_bf16 v[118:121], v[194:197], v[210:213], v[118:121]
	v_mfma_f32_16x16x32_bf16 v[114:117], v[202:205], v[210:213], v[114:117]
	v_mfma_f32_16x16x32_bf16 v[102:105], v[194:197], v[218:221], v[102:105]
	v_mfma_f32_16x16x32_bf16 v[98:101], v[202:205], v[218:221], v[98:101]
	v_mfma_f32_16x16x32_bf16 v[86:89], v[194:197], v[226:229], v[86:89]
	v_mfma_f32_16x16x32_bf16 v[82:85], v[202:205], v[226:229], v[82:85]
	v_mfma_f32_16x16x32_bf16 v[70:73], v[194:197], v[234:237], v[70:73]
	v_mfma_f32_16x16x32_bf16 v[66:69], v[202:205], v[234:237], v[66:69]
	v_mfma_f32_16x16x32_bf16 v[118:121], v[198:201], v[214:217], v[118:121]
	v_mfma_f32_16x16x32_bf16 v[114:117], v[206:209], v[214:217], v[114:117]
	v_mfma_f32_16x16x32_bf16 v[102:105], v[198:201], v[222:225], v[102:105]
	v_mfma_f32_16x16x32_bf16 v[98:101], v[206:209], v[222:225], v[98:101]
	v_mfma_f32_16x16x32_bf16 v[86:89], v[198:201], v[230:233], v[86:89]
	v_mfma_f32_16x16x32_bf16 v[82:85], v[206:209], v[230:233], v[82:85]
	v_mfma_f32_16x16x32_bf16 v[70:73], v[198:201], v[238:241], v[70:73]
	v_mfma_f32_16x16x32_bf16 v[66:69], v[206:209], v[238:241], v[66:69]
	s_barrier
	ds_read_b128 v[210:213], v160 offset:49152
	ds_read_b128 v[214:217], v160 offset:50176
	ds_read_b128 v[218:221], v160 offset:51200
	ds_read_b128 v[222:225], v160 offset:52224
	ds_read_b128 v[226:229], v160 offset:53248
	ds_read_b128 v[230:233], v160 offset:54272
	ds_read_b128 v[234:237], v160 offset:55296
	ds_read_b128 v[238:241], v160 offset:56320
	s_add_i32 s0, s30, s99
	v_lshl_add_u64 v[154:155], v[154:155], 0, s[26:27]
	s_mov_b32 m0, s0
	global_load_lds_dwordx4 v[154:155], off
	v_lshl_add_u64 v[154:155], v[158:159], 0, s[26:27]
	s_add_i32 m0, s0, 0x2000
	s_add_i32 s0, s86, s99
	global_load_lds_dwordx4 v[154:155], off
	v_lshl_add_u64 v[154:155], v[242:243], 0, s[26:27]
	s_mov_b32 m0, s0
	s_nop 0
	global_load_lds_dwordx4 v[154:155], off
	v_lshl_add_u64 v[154:155], v[244:245], 0, s[26:27]
	s_add_i32 m0, s0, 0x2000
	s_nop 0
	global_load_lds_dwordx4 v[154:155], off
	v_lshl_add_u64 v[154:155], v[246:247], 0, s[26:27]
	s_mov_b32 m0, s53
	s_nop 0
	global_load_lds_dwordx4 v[154:155], off
	v_lshl_add_u64 v[154:155], v[248:249], 0, s[26:27]
	s_mov_b32 m0, s56
	s_nop 0
	global_load_lds_dwordx4 v[154:155], off
	s_waitcnt vmcnt(8)
	s_waitcnt lgkmcnt(0)
	s_barrier
	s_waitcnt lgkmcnt(0)
	v_mfma_f32_16x16x32_bf16 v[62:65], v[130:133], v[210:213], v[62:65]
	v_mfma_f32_16x16x32_bf16 v[58:61], v[162:165], v[210:213], v[58:61]
	v_mfma_f32_16x16x32_bf16 v[46:49], v[130:133], v[218:221], v[46:49]
	v_mfma_f32_16x16x32_bf16 v[42:45], v[162:165], v[218:221], v[42:45]
	v_mfma_f32_16x16x32_bf16 v[28:31], v[130:133], v[226:229], v[28:31]
	v_mfma_f32_16x16x32_bf16 v[24:27], v[162:165], v[226:229], v[24:27]
	v_mfma_f32_16x16x32_bf16 v[12:15], v[130:133], v[234:237], v[12:15]
	v_mfma_f32_16x16x32_bf16 v[8:11], v[162:165], v[234:237], v[8:11]
	v_mfma_f32_16x16x32_bf16 v[62:65], v[150:153], v[214:217], v[62:65]
	v_mfma_f32_16x16x32_bf16 v[58:61], v[166:169], v[214:217], v[58:61]
	v_mfma_f32_16x16x32_bf16 v[46:49], v[150:153], v[222:225], v[46:49]
	v_mfma_f32_16x16x32_bf16 v[42:45], v[166:169], v[222:225], v[42:45]
	v_mfma_f32_16x16x32_bf16 v[28:31], v[150:153], v[230:233], v[28:31]
	v_mfma_f32_16x16x32_bf16 v[24:27], v[166:169], v[230:233], v[24:27]
	v_mfma_f32_16x16x32_bf16 v[12:15], v[150:153], v[238:241], v[12:15]
	v_mfma_f32_16x16x32_bf16 v[8:11], v[166:169], v[238:241], v[8:11]
	v_mfma_f32_16x16x32_bf16 v[54:57], v[194:197], v[210:213], v[54:57]
	v_mfma_f32_16x16x32_bf16 v[50:53], v[202:205], v[210:213], v[50:53]
	v_mfma_f32_16x16x32_bf16 v[38:41], v[194:197], v[218:221], v[38:41]
	v_mfma_f32_16x16x32_bf16 v[34:37], v[202:205], v[218:221], v[34:37]
	v_mfma_f32_16x16x32_bf16 v[20:23], v[194:197], v[226:229], v[20:23]
	v_mfma_f32_16x16x32_bf16 v[16:19], v[202:205], v[226:229], v[16:19]
	v_mfma_f32_16x16x32_bf16 v[4:7], v[194:197], v[234:237], v[4:7]
	v_mfma_f32_16x16x32_bf16 v[0:3], v[202:205], v[234:237], v[0:3]
	v_mfma_f32_16x16x32_bf16 v[54:57], v[198:201], v[214:217], v[54:57]
	v_mfma_f32_16x16x32_bf16 v[50:53], v[206:209], v[214:217], v[50:53]
	v_mfma_f32_16x16x32_bf16 v[38:41], v[198:201], v[222:225], v[38:41]
	v_mfma_f32_16x16x32_bf16 v[34:37], v[206:209], v[222:225], v[34:37]
	v_mfma_f32_16x16x32_bf16 v[20:23], v[198:201], v[230:233], v[20:23]
	v_mfma_f32_16x16x32_bf16 v[16:19], v[206:209], v[230:233], v[16:19]
	v_mfma_f32_16x16x32_bf16 v[4:7], v[198:201], v[238:241], v[4:7]
	v_mfma_f32_16x16x32_bf16 v[0:3], v[206:209], v[238:241], v[0:3]
	s_add_u32 s82, s82, 0x100
	s_addc_u32 s83, s83, 0
	s_add_u32 vcc_lo, vcc_lo, 0x100
	s_addc_u32 vcc_hi, vcc_hi, 0
	s_cmp_ge_i32 s22, s94
	s_mov_b32 s84, s22
	s_barrier
	s_cbranch_scc0 .LBB0_264
	s_and_b64 vcc, exec, s[78:79]
	s_cbranch_vccz .LBB0_267
	s_barrier

.LBB0_296:
	ds_read_b128 v[206:209], v149
	ds_read_b128 v[210:213], v149 offset:1024
	ds_read_b128 v[214:217], v149 offset:2048
	ds_read_b128 v[218:221], v149 offset:3072
	ds_read_b128 v[222:225], v149 offset:4096
	ds_read_b128 v[226:229], v149 offset:5120
	ds_read_b128 v[230:233], v149 offset:6144
	ds_read_b128 v[234:237], v149 offset:7168
	s_add_i32 vcc_hi, s82, 2
	s_add_u32 s0, s80, 0x80
	s_addc_u32 s1, s81, 0
	s_add_i32 s30, 0, 0x10000
	s_cmp_eq_u32 s85, s82
	s_cselect_b32 s83, s45, s1
	s_cselect_b32 s82, s44, s0
	v_add_u32_e32 v146, s30, v139
	s_cselect_b32 s1, s79, vcc_lo
	s_cselect_b32 s0, s78, s90
	s_add_i32 s86, 0, 0x14000
	ds_read_b128 v[150:153], v146
	ds_read_b128 v[154:157], v146 offset:1024
	ds_read_b128 v[158:161], v146 offset:2048
	ds_read_b128 v[162:165], v146 offset:3072
	v_add_u32_e32 v146, s86, v139
	ds_read_b128 v[166:169], v146
	ds_read_b128 v[194:197], v146 offset:1024
	ds_read_b128 v[198:201], v146 offset:2048
	ds_read_b128 v[202:205], v146 offset:3072
	v_lshl_add_u64 v[146:147], s[80:81], 0, v[130:131]
	s_add_i32 m0, s54, 0xc000
	global_load_lds_dwordx4 v[146:147], off
	v_lshl_add_u64 v[146:147], s[80:81], 0, v[132:133]
	s_add_i32 m0, s54, 0xe000
	s_nop 0
	global_load_lds_dwordx4 v[146:147], off
	s_waitcnt vmcnt(8)
	s_waitcnt lgkmcnt(0)
	s_barrier
	s_waitcnt lgkmcnt(0)
	v_mfma_f32_16x16x32_bf16 v[126:129], v[150:153], v[206:209], v[126:129]
	v_mfma_f32_16x16x32_bf16 v[118:121], v[158:161], v[206:209], v[118:121]
	v_mfma_f32_16x16x32_bf16 v[110:113], v[150:153], v[214:217], v[110:113]
	v_mfma_f32_16x16x32_bf16 v[102:105], v[158:161], v[214:217], v[102:105]
	v_mfma_f32_16x16x32_bf16 v[94:97], v[150:153], v[222:225], v[94:97]
	v_mfma_f32_16x16x32_bf16 v[86:89], v[158:161], v[222:225], v[86:89]
	v_mfma_f32_16x16x32_bf16 v[78:81], v[150:153], v[230:233], v[78:81]
	v_mfma_f32_16x16x32_bf16 v[70:73], v[158:161], v[230:233], v[70:73]
	v_mfma_f32_16x16x32_bf16 v[126:129], v[154:157], v[210:213], v[126:129]
	v_mfma_f32_16x16x32_bf16 v[118:121], v[162:165], v[210:213], v[118:121]
	v_mfma_f32_16x16x32_bf16 v[110:113], v[154:157], v[218:221], v[110:113]
	v_mfma_f32_16x16x32_bf16 v[102:105], v[162:165], v[218:221], v[102:105]
	v_mfma_f32_16x16x32_bf16 v[94:97], v[154:157], v[226:229], v[94:97]
	v_mfma_f32_16x16x32_bf16 v[86:89], v[162:165], v[226:229], v[86:89]
	v_mfma_f32_16x16x32_bf16 v[78:81], v[154:157], v[234:237], v[78:81]
	v_mfma_f32_16x16x32_bf16 v[70:73], v[162:165], v[234:237], v[70:73]
	v_mfma_f32_16x16x32_bf16 v[122:125], v[166:169], v[206:209], v[122:125]
	v_mfma_f32_16x16x32_bf16 v[114:117], v[198:201], v[206:209], v[114:117]
	v_mfma_f32_16x16x32_bf16 v[106:109], v[166:169], v[214:217], v[106:109]
	v_mfma_f32_16x16x32_bf16 v[98:101], v[198:201], v[214:217], v[98:101]
	v_mfma_f32_16x16x32_bf16 v[90:93], v[166:169], v[222:225], v[90:93]
	v_mfma_f32_16x16x32_bf16 v[82:85], v[198:201], v[222:225], v[82:85]
	v_mfma_f32_16x16x32_bf16 v[74:77], v[166:169], v[230:233], v[74:77]
	v_mfma_f32_16x16x32_bf16 v[66:69], v[198:201], v[230:233], v[66:69]
	v_mfma_f32_16x16x32_bf16 v[122:125], v[194:197], v[210:213], v[122:125]
	v_mfma_f32_16x16x32_bf16 v[114:117], v[202:205], v[210:213], v[114:117]
	v_mfma_f32_16x16x32_bf16 v[106:109], v[194:197], v[218:221], v[106:109]
	v_mfma_f32_16x16x32_bf16 v[98:101], v[202:205], v[218:221], v[98:101]
	v_mfma_f32_16x16x32_bf16 v[90:93], v[194:197], v[226:229], v[90:93]
	v_mfma_f32_16x16x32_bf16 v[82:85], v[202:205], v[226:229], v[82:85]
	v_mfma_f32_16x16x32_bf16 v[74:77], v[194:197], v[234:237], v[74:77]
	v_mfma_f32_16x16x32_bf16 v[66:69], v[202:205], v[234:237], v[66:69]
	s_barrier
	ds_read_b128 v[206:209], v149 offset:16384
	ds_read_b128 v[210:213], v149 offset:17408
	ds_read_b128 v[214:217], v149 offset:18432
	ds_read_b128 v[218:221], v149 offset:19456
	ds_read_b128 v[222:225], v149 offset:20480
	ds_read_b128 v[226:229], v149 offset:21504
	ds_read_b128 v[230:233], v149 offset:22528
	ds_read_b128 v[234:237], v149 offset:23552
	s_add_i32 s30, s30, s25
	v_lshl_add_u64 v[146:147], s[0:1], 0, v[32:33]
	s_mov_b32 m0, s30
	global_load_lds_dwordx4 v[146:147], off
	s_add_i32 m0, s30, 0x2000
	v_lshl_add_u64 v[238:239], s[0:1], 0, v[144:145]
	s_add_u32 s0, s0, s66
	s_addc_u32 s1, s1, s67
	s_add_i32 s30, s86, s25
	global_load_lds_dwordx4 v[238:239], off
	v_lshl_add_u64 v[240:241], s[0:1], 0, v[32:33]
	s_mov_b32 m0, s30
	v_lshl_add_u64 v[242:243], s[0:1], 0, v[144:145]
	global_load_lds_dwordx4 v[240:241], off
	s_add_i32 m0, s30, 0x2000
	v_lshl_add_u64 v[244:245], s[82:83], 0, v[140:141]
	global_load_lds_dwordx4 v[242:243], off
	s_mov_b32 m0, s54
	v_lshl_add_u64 v[246:247], s[82:83], 0, v[142:143]
	global_load_lds_dwordx4 v[244:245], off
	s_mov_b32 m0, s55
	s_nop 0
	global_load_lds_dwordx4 v[246:247], off
	s_waitcnt vmcnt(8)
	s_waitcnt lgkmcnt(0)
	s_barrier
	s_waitcnt lgkmcnt(0)
	v_mfma_f32_16x16x32_bf16 v[62:65], v[150:153], v[206:209], v[62:65]
	v_mfma_f32_16x16x32_bf16 v[54:57], v[158:161], v[206:209], v[54:57]
	v_mfma_f32_16x16x32_bf16 v[46:49], v[150:153], v[214:217], v[46:49]
	v_mfma_f32_16x16x32_bf16 v[38:41], v[158:161], v[214:217], v[38:41]
	v_mfma_f32_16x16x32_bf16 v[28:31], v[150:153], v[222:225], v[28:31]
	v_mfma_f32_16x16x32_bf16 v[20:23], v[158:161], v[222:225], v[20:23]
	v_mfma_f32_16x16x32_bf16 v[12:15], v[150:153], v[230:233], v[12:15]
	v_mfma_f32_16x16x32_bf16 v[4:7], v[158:161], v[230:233], v[4:7]
	v_mfma_f32_16x16x32_bf16 v[62:65], v[154:157], v[210:213], v[62:65]
	v_mfma_f32_16x16x32_bf16 v[54:57], v[162:165], v[210:213], v[54:57]
	v_mfma_f32_16x16x32_bf16 v[46:49], v[154:157], v[218:221], v[46:49]
	v_mfma_f32_16x16x32_bf16 v[38:41], v[162:165], v[218:221], v[38:41]
	v_mfma_f32_16x16x32_bf16 v[28:31], v[154:157], v[226:229], v[28:31]
	v_mfma_f32_16x16x32_bf16 v[20:23], v[162:165], v[226:229], v[20:23]
	v_mfma_f32_16x16x32_bf16 v[12:15], v[154:157], v[234:237], v[12:15]
	v_mfma_f32_16x16x32_bf16 v[4:7], v[162:165], v[234:237], v[4:7]
	v_mfma_f32_16x16x32_bf16 v[58:61], v[166:169], v[206:209], v[58:61]
	v_mfma_f32_16x16x32_bf16 v[50:53], v[198:201], v[206:209], v[50:53]
	v_mfma_f32_16x16x32_bf16 v[42:45], v[166:169], v[214:217], v[42:45]
	v_mfma_f32_16x16x32_bf16 v[34:37], v[198:201], v[214:217], v[34:37]
	v_mfma_f32_16x16x32_bf16 v[24:27], v[166:169], v[222:225], v[24:27]
	v_mfma_f32_16x16x32_bf16 v[16:19], v[198:201], v[222:225], v[16:19]
	v_mfma_f32_16x16x32_bf16 v[8:11], v[166:169], v[230:233], v[8:11]
	v_mfma_f32_16x16x32_bf16 v[0:3], v[198:201], v[230:233], v[0:3]
	v_mfma_f32_16x16x32_bf16 v[58:61], v[194:197], v[210:213], v[58:61]
	v_mfma_f32_16x16x32_bf16 v[50:53], v[202:205], v[210:213], v[50:53]
	v_mfma_f32_16x16x32_bf16 v[42:45], v[194:197], v[218:221], v[42:45]
	v_mfma_f32_16x16x32_bf16 v[34:37], v[202:205], v[218:221], v[34:37]
	v_mfma_f32_16x16x32_bf16 v[24:27], v[194:197], v[226:229], v[24:27]
	v_mfma_f32_16x16x32_bf16 v[16:19], v[202:205], v[226:229], v[16:19]
	v_mfma_f32_16x16x32_bf16 v[8:11], v[194:197], v[234:237], v[8:11]
	v_mfma_f32_16x16x32_bf16 v[0:3], v[202:205], v[234:237], v[0:3]
	s_barrier
	ds_read_b128 v[206:209], v149 offset:32768
	ds_read_b128 v[210:213], v149 offset:33792
	ds_read_b128 v[214:217], v149 offset:34816
	ds_read_b128 v[218:221], v149 offset:35840
	ds_read_b128 v[222:225], v149 offset:36864
	ds_read_b128 v[226:229], v149 offset:37888
	ds_read_b128 v[230:233], v149 offset:38912
	ds_read_b128 v[234:237], v149 offset:39936
	s_add_i32 s30, 0, 0x18000
	s_add_i32 s86, 0, 0x1c000
	v_add_u32_e32 v162, s30, v139
	v_add_u32_e32 v181, s86, v139
	ds_read_b128 v[150:153], v162
	ds_read_b128 v[154:157], v162 offset:1024
	ds_read_b128 v[158:161], v162 offset:2048
	ds_read_b128 v[162:165], v162 offset:3072
	ds_read_b128 v[166:169], v181
	ds_read_b128 v[194:197], v181 offset:1024
	ds_read_b128 v[198:201], v181 offset:2048
	ds_read_b128 v[202:205], v181 offset:3072
	s_add_u32 s0, s82, s66
	s_addc_u32 s1, s83, s67
	s_mov_b32 m0, s56
	v_lshl_add_u64 v[248:249], s[0:1], 0, v[140:141]
	global_load_lds_dwordx4 v[248:249], off
	v_lshl_add_u64 v[248:249], s[0:1], 0, v[142:143]
	s_mov_b32 m0, s57
	s_nop 0
	global_load_lds_dwordx4 v[248:249], off
	s_waitcnt vmcnt(8)
	s_waitcnt lgkmcnt(0)
	s_barrier
	s_waitcnt lgkmcnt(0)
	v_mfma_f32_16x16x32_bf16 v[126:129], v[150:153], v[206:209], v[126:129]
	v_mfma_f32_16x16x32_bf16 v[118:121], v[158:161], v[206:209], v[118:121]
	v_mfma_f32_16x16x32_bf16 v[110:113], v[150:153], v[214:217], v[110:113]
	v_mfma_f32_16x16x32_bf16 v[102:105], v[158:161], v[214:217], v[102:105]
	v_mfma_f32_16x16x32_bf16 v[94:97], v[150:153], v[222:225], v[94:97]
	v_mfma_f32_16x16x32_bf16 v[86:89], v[158:161], v[222:225], v[86:89]
	v_mfma_f32_16x16x32_bf16 v[78:81], v[150:153], v[230:233], v[78:81]
	v_mfma_f32_16x16x32_bf16 v[70:73], v[158:161], v[230:233], v[70:73]
	v_mfma_f32_16x16x32_bf16 v[126:129], v[154:157], v[210:213], v[126:129]
	v_mfma_f32_16x16x32_bf16 v[118:121], v[162:165], v[210:213], v[118:121]
	v_mfma_f32_16x16x32_bf16 v[110:113], v[154:157], v[218:221], v[110:113]
	v_mfma_f32_16x16x32_bf16 v[102:105], v[162:165], v[218:221], v[102:105]
	v_mfma_f32_16x16x32_bf16 v[94:97], v[154:157], v[226:229], v[94:97]
	v_mfma_f32_16x16x32_bf16 v[86:89], v[162:165], v[226:229], v[86:89]
	v_mfma_f32_16x16x32_bf16 v[78:81], v[154:157], v[234:237], v[78:81]
	v_mfma_f32_16x16x32_bf16 v[70:73], v[162:165], v[234:237], v[70:73]
	v_mfma_f32_16x16x32_bf16 v[122:125], v[166:169], v[206:209], v[122:125]
	v_mfma_f32_16x16x32_bf16 v[114:117], v[198:201], v[206:209], v[114:117]
	v_mfma_f32_16x16x32_bf16 v[106:109], v[166:169], v[214:217], v[106:109]
	v_mfma_f32_16x16x32_bf16 v[98:101], v[198:201], v[214:217], v[98:101]
	v_mfma_f32_16x16x32_bf16 v[90:93], v[166:169], v[222:225], v[90:93]
	v_mfma_f32_16x16x32_bf16 v[82:85], v[198:201], v[222:225], v[82:85]
	v_mfma_f32_16x16x32_bf16 v[74:77], v[166:169], v[230:233], v[74:77]
	v_mfma_f32_16x16x32_bf16 v[66:69], v[198:201], v[230:233], v[66:69]
	v_mfma_f32_16x16x32_bf16 v[122:125], v[194:197], v[210:213], v[122:125]
	v_mfma_f32_16x16x32_bf16 v[114:117], v[202:205], v[210:213], v[114:117]
	v_mfma_f32_16x16x32_bf16 v[106:109], v[194:197], v[218:221], v[106:109]
	v_mfma_f32_16x16x32_bf16 v[98:101], v[202:205], v[218:221], v[98:101]
	v_mfma_f32_16x16x32_bf16 v[90:93], v[194:197], v[226:229], v[90:93]
	v_mfma_f32_16x16x32_bf16 v[82:85], v[202:205], v[226:229], v[82:85]
	v_mfma_f32_16x16x32_bf16 v[74:77], v[194:197], v[234:237], v[74:77]
	v_mfma_f32_16x16x32_bf16 v[66:69], v[202:205], v[234:237], v[66:69]
	s_barrier
	ds_read_b128 v[206:209], v149 offset:49152
	ds_read_b128 v[210:213], v149 offset:50176
	ds_read_b128 v[214:217], v149 offset:51200
	ds_read_b128 v[218:221], v149 offset:52224
	ds_read_b128 v[222:225], v149 offset:53248
	ds_read_b128 v[226:229], v149 offset:54272
	ds_read_b128 v[230:233], v149 offset:55296
	ds_read_b128 v[234:237], v149 offset:56320
	s_add_i32 s0, s30, s25
	v_lshl_add_u64 v[146:147], v[146:147], 0, s[26:27]
	s_mov_b32 m0, s0
	global_load_lds_dwordx4 v[146:147], off
	v_lshl_add_u64 v[146:147], v[238:239], 0, s[26:27]
	s_add_i32 m0, s0, 0x2000
	s_add_i32 s0, s86, s25
	global_load_lds_dwordx4 v[146:147], off
	v_lshl_add_u64 v[146:147], v[240:241], 0, s[26:27]
	s_mov_b32 m0, s0
	s_nop 0
	global_load_lds_dwordx4 v[146:147], off
	v_lshl_add_u64 v[146:147], v[242:243], 0, s[26:27]
	s_add_i32 m0, s0, 0x2000
	s_nop 0
	global_load_lds_dwordx4 v[146:147], off
	v_lshl_add_u64 v[146:147], v[244:245], 0, s[26:27]
	s_mov_b32 m0, s71
	s_nop 0
	global_load_lds_dwordx4 v[146:147], off
	v_lshl_add_u64 v[146:147], v[246:247], 0, s[26:27]
	s_mov_b32 m0, s84
	s_nop 0
	global_load_lds_dwordx4 v[146:147], off
	s_waitcnt vmcnt(8)
	s_waitcnt lgkmcnt(0)
	s_barrier
	s_waitcnt lgkmcnt(0)
	v_mfma_f32_16x16x32_bf16 v[62:65], v[150:153], v[206:209], v[62:65]
	v_mfma_f32_16x16x32_bf16 v[54:57], v[158:161], v[206:209], v[54:57]
	v_mfma_f32_16x16x32_bf16 v[46:49], v[150:153], v[214:217], v[46:49]
	v_mfma_f32_16x16x32_bf16 v[38:41], v[158:161], v[214:217], v[38:41]
	v_mfma_f32_16x16x32_bf16 v[28:31], v[150:153], v[222:225], v[28:31]
	v_mfma_f32_16x16x32_bf16 v[20:23], v[158:161], v[222:225], v[20:23]
	v_mfma_f32_16x16x32_bf16 v[12:15], v[150:153], v[230:233], v[12:15]
	v_mfma_f32_16x16x32_bf16 v[4:7], v[158:161], v[230:233], v[4:7]
	v_mfma_f32_16x16x32_bf16 v[62:65], v[154:157], v[210:213], v[62:65]
	v_mfma_f32_16x16x32_bf16 v[54:57], v[162:165], v[210:213], v[54:57]
	v_mfma_f32_16x16x32_bf16 v[46:49], v[154:157], v[218:221], v[46:49]
	v_mfma_f32_16x16x32_bf16 v[38:41], v[162:165], v[218:221], v[38:41]
	v_mfma_f32_16x16x32_bf16 v[28:31], v[154:157], v[226:229], v[28:31]
	v_mfma_f32_16x16x32_bf16 v[20:23], v[162:165], v[226:229], v[20:23]
	v_mfma_f32_16x16x32_bf16 v[12:15], v[154:157], v[234:237], v[12:15]
	v_mfma_f32_16x16x32_bf16 v[4:7], v[162:165], v[234:237], v[4:7]
	v_mfma_f32_16x16x32_bf16 v[58:61], v[166:169], v[206:209], v[58:61]
	v_mfma_f32_16x16x32_bf16 v[50:53], v[198:201], v[206:209], v[50:53]
	v_mfma_f32_16x16x32_bf16 v[42:45], v[166:169], v[214:217], v[42:45]
	v_mfma_f32_16x16x32_bf16 v[34:37], v[198:201], v[214:217], v[34:37]
	v_mfma_f32_16x16x32_bf16 v[24:27], v[166:169], v[222:225], v[24:27]
	v_mfma_f32_16x16x32_bf16 v[16:19], v[198:201], v[222:225], v[16:19]
	v_mfma_f32_16x16x32_bf16 v[8:11], v[166:169], v[230:233], v[8:11]
	v_mfma_f32_16x16x32_bf16 v[0:3], v[198:201], v[230:233], v[0:3]
	v_mfma_f32_16x16x32_bf16 v[58:61], v[194:197], v[210:213], v[58:61]
	v_mfma_f32_16x16x32_bf16 v[50:53], v[202:205], v[210:213], v[50:53]
	v_mfma_f32_16x16x32_bf16 v[42:45], v[194:197], v[218:221], v[42:45]
	v_mfma_f32_16x16x32_bf16 v[34:37], v[202:205], v[218:221], v[34:37]
	v_mfma_f32_16x16x32_bf16 v[24:27], v[194:197], v[226:229], v[24:27]
	v_mfma_f32_16x16x32_bf16 v[16:19], v[202:205], v[226:229], v[16:19]
	v_mfma_f32_16x16x32_bf16 v[8:11], v[194:197], v[234:237], v[8:11]
	v_mfma_f32_16x16x32_bf16 v[0:3], v[202:205], v[234:237], v[0:3]
	s_add_u32 s80, s80, 0x100
	s_addc_u32 s81, s81, 0
	s_add_u32 s90, s90, 0x100
	s_addc_u32 vcc_lo, vcc_lo, 0
	s_cmp_ge_i32 vcc_hi, s94
	s_mov_b32 s82, vcc_hi
	s_barrier
	s_cbranch_scc0 .LBB0_296
	s_and_b64 vcc, exec, s[76:77]
	s_cbranch_vccz .LBB0_299
	s_barrier

.LBB0_327:
	ds_read_b128 v[206:209], v151
	ds_read_b128 v[210:213], v151 offset:1024
	ds_read_b128 v[214:217], v151 offset:2048
	ds_read_b128 v[218:221], v151 offset:3072
	ds_read_b128 v[222:225], v151 offset:4096
	ds_read_b128 v[226:229], v151 offset:5120
	ds_read_b128 v[230:233], v151 offset:6144
	ds_read_b128 v[234:237], v151 offset:7168
	s_add_i32 s0, s80, 2
	s_add_u32 s1, s78, 0x80
	s_addc_u32 s30, s79, 0
	s_add_i32 s86, 0, 0x10000
	s_cmp_eq_u32 s82, s80
	s_cselect_b32 s81, s45, s30
	s_cselect_b32 s80, s44, s1
	s_cselect_b32 s99, s77, s97
	s_cselect_b32 s98, s76, s96
	s_add_i32 s1, 0, 0x14000
	v_add_u32_e32 v160, s86, v139
	v_add_u32_e32 v168, s1, v139
	ds_read_b128 v[146:149], v160
	ds_read_b128 v[152:155], v160 offset:1024
	ds_read_b128 v[156:159], v160 offset:2048
	ds_read_b128 v[160:163], v160 offset:3072
	ds_read_b128 v[164:167], v168
	ds_read_b128 v[194:197], v168 offset:1024
	ds_read_b128 v[198:201], v168 offset:2048
	ds_read_b128 v[202:205], v168 offset:3072
	v_lshl_add_u64 v[168:169], s[78:79], 0, v[130:131]
	s_add_i32 m0, s53, 0xc000
	global_load_lds_dwordx4 v[168:169], off
	v_lshl_add_u64 v[168:169], s[78:79], 0, v[132:133]
	s_add_i32 m0, s53, 0xe000
	s_nop 0
	global_load_lds_dwordx4 v[168:169], off
	s_waitcnt vmcnt(8)
	s_waitcnt lgkmcnt(0)
	s_barrier
	s_waitcnt lgkmcnt(0)
	v_mfma_f32_16x16x32_bf16 v[126:129], v[146:149], v[206:209], v[126:129]
	v_mfma_f32_16x16x32_bf16 v[122:125], v[156:159], v[206:209], v[122:125]
	v_mfma_f32_16x16x32_bf16 v[110:113], v[146:149], v[214:217], v[110:113]
	v_mfma_f32_16x16x32_bf16 v[106:109], v[156:159], v[214:217], v[106:109]
	v_mfma_f32_16x16x32_bf16 v[94:97], v[146:149], v[222:225], v[94:97]
	v_mfma_f32_16x16x32_bf16 v[90:93], v[156:159], v[222:225], v[90:93]
	v_mfma_f32_16x16x32_bf16 v[78:81], v[146:149], v[230:233], v[78:81]
	v_mfma_f32_16x16x32_bf16 v[74:77], v[156:159], v[230:233], v[74:77]
	v_mfma_f32_16x16x32_bf16 v[126:129], v[152:155], v[210:213], v[126:129]
	v_mfma_f32_16x16x32_bf16 v[122:125], v[160:163], v[210:213], v[122:125]
	v_mfma_f32_16x16x32_bf16 v[110:113], v[152:155], v[218:221], v[110:113]
	v_mfma_f32_16x16x32_bf16 v[106:109], v[160:163], v[218:221], v[106:109]
	v_mfma_f32_16x16x32_bf16 v[94:97], v[152:155], v[226:229], v[94:97]
	v_mfma_f32_16x16x32_bf16 v[90:93], v[160:163], v[226:229], v[90:93]
	v_mfma_f32_16x16x32_bf16 v[78:81], v[152:155], v[234:237], v[78:81]
	v_mfma_f32_16x16x32_bf16 v[74:77], v[160:163], v[234:237], v[74:77]
	v_mfma_f32_16x16x32_bf16 v[118:121], v[164:167], v[206:209], v[118:121]
	v_mfma_f32_16x16x32_bf16 v[114:117], v[198:201], v[206:209], v[114:117]
	v_mfma_f32_16x16x32_bf16 v[102:105], v[164:167], v[214:217], v[102:105]
	v_mfma_f32_16x16x32_bf16 v[98:101], v[198:201], v[214:217], v[98:101]
	v_mfma_f32_16x16x32_bf16 v[86:89], v[164:167], v[222:225], v[86:89]
	v_mfma_f32_16x16x32_bf16 v[82:85], v[198:201], v[222:225], v[82:85]
	v_mfma_f32_16x16x32_bf16 v[70:73], v[164:167], v[230:233], v[70:73]
	v_mfma_f32_16x16x32_bf16 v[66:69], v[198:201], v[230:233], v[66:69]
	v_mfma_f32_16x16x32_bf16 v[118:121], v[194:197], v[210:213], v[118:121]
	v_mfma_f32_16x16x32_bf16 v[114:117], v[202:205], v[210:213], v[114:117]
	v_mfma_f32_16x16x32_bf16 v[102:105], v[194:197], v[218:221], v[102:105]
	v_mfma_f32_16x16x32_bf16 v[98:101], v[202:205], v[218:221], v[98:101]
	v_mfma_f32_16x16x32_bf16 v[86:89], v[194:197], v[226:229], v[86:89]
	v_mfma_f32_16x16x32_bf16 v[82:85], v[202:205], v[226:229], v[82:85]
	v_mfma_f32_16x16x32_bf16 v[70:73], v[194:197], v[234:237], v[70:73]
	v_mfma_f32_16x16x32_bf16 v[66:69], v[202:205], v[234:237], v[66:69]
	s_barrier
	ds_read_b128 v[206:209], v151 offset:16384
	ds_read_b128 v[210:213], v151 offset:17408
	ds_read_b128 v[214:217], v151 offset:18432
	ds_read_b128 v[218:221], v151 offset:19456
	ds_read_b128 v[222:225], v151 offset:20480
	ds_read_b128 v[226:229], v151 offset:21504
	ds_read_b128 v[230:233], v151 offset:22528
	ds_read_b128 v[234:237], v151 offset:23552
	s_add_i32 s30, s86, s23
	v_lshl_add_u64 v[168:169], s[98:99], 0, v[32:33]
	s_mov_b32 m0, s30
	global_load_lds_dwordx4 v[168:169], off
	s_add_i32 m0, s30, 0x2000
	v_lshl_add_u64 v[238:239], s[98:99], 0, v[144:145]
	s_add_u32 s98, s98, s66
	s_addc_u32 s99, s99, s67
	s_add_i32 s1, s1, s23
	global_load_lds_dwordx4 v[238:239], off
	v_lshl_add_u64 v[240:241], s[98:99], 0, v[32:33]
	s_mov_b32 m0, s1
	v_lshl_add_u64 v[242:243], s[98:99], 0, v[144:145]
	global_load_lds_dwordx4 v[240:241], off
	s_add_i32 m0, s1, 0x2000
	v_lshl_add_u64 v[244:245], s[80:81], 0, v[140:141]
	global_load_lds_dwordx4 v[242:243], off
	s_mov_b32 m0, s53
	v_lshl_add_u64 v[246:247], s[80:81], 0, v[142:143]
	global_load_lds_dwordx4 v[244:245], off
	s_mov_b32 m0, s54
	s_nop 0
	global_load_lds_dwordx4 v[246:247], off
	s_waitcnt vmcnt(8)
	s_waitcnt lgkmcnt(0)
	s_barrier
	s_waitcnt lgkmcnt(0)
	v_mfma_f32_16x16x32_bf16 v[62:65], v[146:149], v[206:209], v[62:65]
	v_mfma_f32_16x16x32_bf16 v[58:61], v[156:159], v[206:209], v[58:61]
	v_mfma_f32_16x16x32_bf16 v[46:49], v[146:149], v[214:217], v[46:49]
	v_mfma_f32_16x16x32_bf16 v[42:45], v[156:159], v[214:217], v[42:45]
	v_mfma_f32_16x16x32_bf16 v[28:31], v[146:149], v[222:225], v[28:31]
	v_mfma_f32_16x16x32_bf16 v[24:27], v[156:159], v[222:225], v[24:27]
	v_mfma_f32_16x16x32_bf16 v[12:15], v[146:149], v[230:233], v[12:15]
	v_mfma_f32_16x16x32_bf16 v[8:11], v[156:159], v[230:233], v[8:11]
	v_mfma_f32_16x16x32_bf16 v[62:65], v[152:155], v[210:213], v[62:65]
	v_mfma_f32_16x16x32_bf16 v[58:61], v[160:163], v[210:213], v[58:61]
	v_mfma_f32_16x16x32_bf16 v[46:49], v[152:155], v[218:221], v[46:49]
	v_mfma_f32_16x16x32_bf16 v[42:45], v[160:163], v[218:221], v[42:45]
	v_mfma_f32_16x16x32_bf16 v[28:31], v[152:155], v[226:229], v[28:31]
	v_mfma_f32_16x16x32_bf16 v[24:27], v[160:163], v[226:229], v[24:27]
	v_mfma_f32_16x16x32_bf16 v[12:15], v[152:155], v[234:237], v[12:15]
	v_mfma_f32_16x16x32_bf16 v[8:11], v[160:163], v[234:237], v[8:11]
	v_mfma_f32_16x16x32_bf16 v[54:57], v[164:167], v[206:209], v[54:57]
	v_mfma_f32_16x16x32_bf16 v[50:53], v[198:201], v[206:209], v[50:53]
	v_mfma_f32_16x16x32_bf16 v[38:41], v[164:167], v[214:217], v[38:41]
	v_mfma_f32_16x16x32_bf16 v[34:37], v[198:201], v[214:217], v[34:37]
	v_mfma_f32_16x16x32_bf16 v[20:23], v[164:167], v[222:225], v[20:23]
	v_mfma_f32_16x16x32_bf16 v[16:19], v[198:201], v[222:225], v[16:19]
	v_mfma_f32_16x16x32_bf16 v[4:7], v[164:167], v[230:233], v[4:7]
	v_mfma_f32_16x16x32_bf16 v[0:3], v[198:201], v[230:233], v[0:3]
	v_mfma_f32_16x16x32_bf16 v[54:57], v[194:197], v[210:213], v[54:57]
	v_mfma_f32_16x16x32_bf16 v[50:53], v[202:205], v[210:213], v[50:53]
	v_mfma_f32_16x16x32_bf16 v[38:41], v[194:197], v[218:221], v[38:41]
	v_mfma_f32_16x16x32_bf16 v[34:37], v[202:205], v[218:221], v[34:37]
	v_mfma_f32_16x16x32_bf16 v[20:23], v[194:197], v[226:229], v[20:23]
	v_mfma_f32_16x16x32_bf16 v[16:19], v[202:205], v[226:229], v[16:19]
	v_mfma_f32_16x16x32_bf16 v[4:7], v[194:197], v[234:237], v[4:7]
	v_mfma_f32_16x16x32_bf16 v[0:3], v[202:205], v[234:237], v[0:3]
	s_barrier
	ds_read_b128 v[206:209], v151 offset:32768
	ds_read_b128 v[210:213], v151 offset:33792
	ds_read_b128 v[214:217], v151 offset:34816
	ds_read_b128 v[218:221], v151 offset:35840
	ds_read_b128 v[222:225], v151 offset:36864
	ds_read_b128 v[226:229], v151 offset:37888
	ds_read_b128 v[230:233], v151 offset:38912
	ds_read_b128 v[234:237], v151 offset:39936
	s_add_i32 s1, 0, 0x18000
	s_add_i32 s30, 0, 0x1c000
	v_add_u32_e32 v160, s1, v139
	v_add_u32_e32 v181, s30, v139
	ds_read_b128 v[146:149], v160
	ds_read_b128 v[152:155], v160 offset:1024
	ds_read_b128 v[156:159], v160 offset:2048
	ds_read_b128 v[160:163], v160 offset:3072
	ds_read_b128 v[164:167], v181
	ds_read_b128 v[194:197], v181 offset:1024
	ds_read_b128 v[198:201], v181 offset:2048
	ds_read_b128 v[202:205], v181 offset:3072
	s_add_u32 s80, s80, s66
	s_addc_u32 s81, s81, s67
	s_mov_b32 m0, s55
	v_lshl_add_u64 v[248:249], s[80:81], 0, v[140:141]
	global_load_lds_dwordx4 v[248:249], off
	v_lshl_add_u64 v[248:249], s[80:81], 0, v[142:143]
	s_mov_b32 m0, s56
	s_nop 0
	global_load_lds_dwordx4 v[248:249], off
	s_waitcnt vmcnt(8)
	s_waitcnt lgkmcnt(0)
	s_barrier
	s_waitcnt lgkmcnt(0)
	v_mfma_f32_16x16x32_bf16 v[126:129], v[146:149], v[206:209], v[126:129]
	v_mfma_f32_16x16x32_bf16 v[122:125], v[156:159], v[206:209], v[122:125]
	v_mfma_f32_16x16x32_bf16 v[110:113], v[146:149], v[214:217], v[110:113]
	v_mfma_f32_16x16x32_bf16 v[106:109], v[156:159], v[214:217], v[106:109]
	v_mfma_f32_16x16x32_bf16 v[94:97], v[146:149], v[222:225], v[94:97]
	v_mfma_f32_16x16x32_bf16 v[90:93], v[156:159], v[222:225], v[90:93]
	v_mfma_f32_16x16x32_bf16 v[78:81], v[146:149], v[230:233], v[78:81]
	v_mfma_f32_16x16x32_bf16 v[74:77], v[156:159], v[230:233], v[74:77]
	v_mfma_f32_16x16x32_bf16 v[126:129], v[152:155], v[210:213], v[126:129]
	v_mfma_f32_16x16x32_bf16 v[122:125], v[160:163], v[210:213], v[122:125]
	v_mfma_f32_16x16x32_bf16 v[110:113], v[152:155], v[218:221], v[110:113]
	v_mfma_f32_16x16x32_bf16 v[106:109], v[160:163], v[218:221], v[106:109]
	v_mfma_f32_16x16x32_bf16 v[94:97], v[152:155], v[226:229], v[94:97]
	v_mfma_f32_16x16x32_bf16 v[90:93], v[160:163], v[226:229], v[90:93]
	v_mfma_f32_16x16x32_bf16 v[78:81], v[152:155], v[234:237], v[78:81]
	v_mfma_f32_16x16x32_bf16 v[74:77], v[160:163], v[234:237], v[74:77]
	v_mfma_f32_16x16x32_bf16 v[118:121], v[164:167], v[206:209], v[118:121]
	v_mfma_f32_16x16x32_bf16 v[114:117], v[198:201], v[206:209], v[114:117]
	v_mfma_f32_16x16x32_bf16 v[102:105], v[164:167], v[214:217], v[102:105]
	v_mfma_f32_16x16x32_bf16 v[98:101], v[198:201], v[214:217], v[98:101]
	v_mfma_f32_16x16x32_bf16 v[86:89], v[164:167], v[222:225], v[86:89]
	v_mfma_f32_16x16x32_bf16 v[82:85], v[198:201], v[222:225], v[82:85]
	v_mfma_f32_16x16x32_bf16 v[70:73], v[164:167], v[230:233], v[70:73]
	v_mfma_f32_16x16x32_bf16 v[66:69], v[198:201], v[230:233], v[66:69]
	v_mfma_f32_16x16x32_bf16 v[118:121], v[194:197], v[210:213], v[118:121]
	v_mfma_f32_16x16x32_bf16 v[114:117], v[202:205], v[210:213], v[114:117]
	v_mfma_f32_16x16x32_bf16 v[102:105], v[194:197], v[218:221], v[102:105]
	v_mfma_f32_16x16x32_bf16 v[98:101], v[202:205], v[218:221], v[98:101]
	v_mfma_f32_16x16x32_bf16 v[86:89], v[194:197], v[226:229], v[86:89]
	v_mfma_f32_16x16x32_bf16 v[82:85], v[202:205], v[226:229], v[82:85]
	v_mfma_f32_16x16x32_bf16 v[70:73], v[194:197], v[234:237], v[70:73]
	v_mfma_f32_16x16x32_bf16 v[66:69], v[202:205], v[234:237], v[66:69]
	s_barrier
	ds_read_b128 v[206:209], v151 offset:49152
	ds_read_b128 v[210:213], v151 offset:50176
	ds_read_b128 v[214:217], v151 offset:51200
	ds_read_b128 v[218:221], v151 offset:52224
	ds_read_b128 v[222:225], v151 offset:53248
	ds_read_b128 v[226:229], v151 offset:54272
	ds_read_b128 v[230:233], v151 offset:55296
	ds_read_b128 v[234:237], v151 offset:56320
	s_add_i32 s1, s1, s23
	v_lshl_add_u64 v[168:169], v[168:169], 0, s[26:27]
	s_mov_b32 m0, s1
	global_load_lds_dwordx4 v[168:169], off
	v_lshl_add_u64 v[168:169], v[238:239], 0, s[26:27]
	s_add_i32 m0, s1, 0x2000
	s_add_i32 s1, s30, s23
	global_load_lds_dwordx4 v[168:169], off
	v_lshl_add_u64 v[168:169], v[240:241], 0, s[26:27]
	s_mov_b32 m0, s1
	s_nop 0
	global_load_lds_dwordx4 v[168:169], off
	v_lshl_add_u64 v[168:169], v[242:243], 0, s[26:27]
	s_add_i32 m0, s1, 0x2000
	s_nop 0
	global_load_lds_dwordx4 v[168:169], off
	v_lshl_add_u64 v[168:169], v[244:245], 0, s[26:27]
	s_mov_b32 m0, s57
	s_nop 0
	global_load_lds_dwordx4 v[168:169], off
	v_lshl_add_u64 v[168:169], v[246:247], 0, s[26:27]
	s_mov_b32 m0, s71
	s_nop 0
	global_load_lds_dwordx4 v[168:169], off
	s_waitcnt vmcnt(8)
	s_waitcnt lgkmcnt(0)
	s_barrier
	s_waitcnt lgkmcnt(0)
	v_mfma_f32_16x16x32_bf16 v[62:65], v[146:149], v[206:209], v[62:65]
	v_mfma_f32_16x16x32_bf16 v[58:61], v[156:159], v[206:209], v[58:61]
	v_mfma_f32_16x16x32_bf16 v[46:49], v[146:149], v[214:217], v[46:49]
	v_mfma_f32_16x16x32_bf16 v[42:45], v[156:159], v[214:217], v[42:45]
	v_mfma_f32_16x16x32_bf16 v[28:31], v[146:149], v[222:225], v[28:31]
	v_mfma_f32_16x16x32_bf16 v[24:27], v[156:159], v[222:225], v[24:27]
	v_mfma_f32_16x16x32_bf16 v[12:15], v[146:149], v[230:233], v[12:15]
	v_mfma_f32_16x16x32_bf16 v[8:11], v[156:159], v[230:233], v[8:11]
	v_mfma_f32_16x16x32_bf16 v[62:65], v[152:155], v[210:213], v[62:65]
	v_mfma_f32_16x16x32_bf16 v[58:61], v[160:163], v[210:213], v[58:61]
	v_mfma_f32_16x16x32_bf16 v[46:49], v[152:155], v[218:221], v[46:49]
	v_mfma_f32_16x16x32_bf16 v[42:45], v[160:163], v[218:221], v[42:45]
	v_mfma_f32_16x16x32_bf16 v[28:31], v[152:155], v[226:229], v[28:31]
	v_mfma_f32_16x16x32_bf16 v[24:27], v[160:163], v[226:229], v[24:27]
	v_mfma_f32_16x16x32_bf16 v[12:15], v[152:155], v[234:237], v[12:15]
	v_mfma_f32_16x16x32_bf16 v[8:11], v[160:163], v[234:237], v[8:11]
	v_mfma_f32_16x16x32_bf16 v[54:57], v[164:167], v[206:209], v[54:57]
	v_mfma_f32_16x16x32_bf16 v[50:53], v[198:201], v[206:209], v[50:53]
	v_mfma_f32_16x16x32_bf16 v[38:41], v[164:167], v[214:217], v[38:41]
	v_mfma_f32_16x16x32_bf16 v[34:37], v[198:201], v[214:217], v[34:37]
	v_mfma_f32_16x16x32_bf16 v[20:23], v[164:167], v[222:225], v[20:23]
	v_mfma_f32_16x16x32_bf16 v[16:19], v[198:201], v[222:225], v[16:19]
	v_mfma_f32_16x16x32_bf16 v[4:7], v[164:167], v[230:233], v[4:7]
	v_mfma_f32_16x16x32_bf16 v[0:3], v[198:201], v[230:233], v[0:3]
	v_mfma_f32_16x16x32_bf16 v[54:57], v[194:197], v[210:213], v[54:57]
	v_mfma_f32_16x16x32_bf16 v[50:53], v[202:205], v[210:213], v[50:53]
	v_mfma_f32_16x16x32_bf16 v[38:41], v[194:197], v[218:221], v[38:41]
	v_mfma_f32_16x16x32_bf16 v[34:37], v[202:205], v[218:221], v[34:37]
	v_mfma_f32_16x16x32_bf16 v[20:23], v[194:197], v[226:229], v[20:23]
	v_mfma_f32_16x16x32_bf16 v[16:19], v[202:205], v[226:229], v[16:19]
	v_mfma_f32_16x16x32_bf16 v[4:7], v[194:197], v[234:237], v[4:7]
	v_mfma_f32_16x16x32_bf16 v[0:3], v[202:205], v[234:237], v[0:3]
	s_add_u32 s78, s78, 0x100
	s_addc_u32 s79, s79, 0
	s_add_u32 s96, s96, 0x100
	s_addc_u32 s97, s97, 0
	s_cmp_ge_i32 s0, s94
	s_mov_b32 s80, s0
	s_barrier
	s_cbranch_scc0 .LBB0_327
	s_and_b64 vcc, exec, s[74:75]
	s_cbranch_vccz .LBB0_330
	s_barrier

.LBB0_356:
	ds_read_b128 v[206:209], v147
	ds_read_b128 v[210:213], v147 offset:1024
	ds_read_b128 v[214:217], v147 offset:2048
	ds_read_b128 v[218:221], v147 offset:3072
	ds_read_b128 v[222:225], v147 offset:4096
	ds_read_b128 v[226:229], v147 offset:5120
	ds_read_b128 v[230:233], v147 offset:6144
	ds_read_b128 v[234:237], v147 offset:7168
	s_add_i32 s91, s76, 2
	s_add_u32 s0, s74, 0x80
	s_addc_u32 s1, s75, 0
	s_add_i32 s95, 0, 0x10000
	s_cmp_eq_u32 s81, s76
	s_cselect_b32 s77, s43, s1
	s_cselect_b32 s76, s42, s0
	s_cselect_b32 s1, s71, s90
	s_cselect_b32 s0, s70, s85
	s_add_i32 s96, 0, 0x14000
	v_add_u32_e32 v160, s95, v139
	v_add_u32_e32 v168, s96, v139
	ds_read_b128 v[148:151], v160
	ds_read_b128 v[152:155], v160 offset:1024
	ds_read_b128 v[156:159], v160 offset:2048
	ds_read_b128 v[160:163], v160 offset:3072
	ds_read_b128 v[164:167], v168
	ds_read_b128 v[194:197], v168 offset:1024
	ds_read_b128 v[198:201], v168 offset:2048
	ds_read_b128 v[202:205], v168 offset:3072
	v_lshl_add_u64 v[168:169], s[74:75], 0, v[130:131]
	s_add_i32 m0, s53, 0xc000
	global_load_lds_dwordx4 v[168:169], off
	v_lshl_add_u64 v[168:169], s[74:75], 0, v[132:133]
	s_add_i32 m0, s53, 0xe000
	s_nop 0
	global_load_lds_dwordx4 v[168:169], off
	s_waitcnt vmcnt(8)
	s_waitcnt lgkmcnt(0)
	s_barrier
	s_waitcnt lgkmcnt(0)
	v_mfma_f32_16x16x32_bf16 v[126:129], v[148:151], v[206:209], v[126:129]
	v_mfma_f32_16x16x32_bf16 v[122:125], v[156:159], v[206:209], v[122:125]
	v_mfma_f32_16x16x32_bf16 v[118:121], v[148:151], v[214:217], v[118:121]
	v_mfma_f32_16x16x32_bf16 v[114:117], v[156:159], v[214:217], v[114:117]
	v_mfma_f32_16x16x32_bf16 v[102:105], v[148:151], v[222:225], v[102:105]
	v_mfma_f32_16x16x32_bf16 v[98:101], v[156:159], v[222:225], v[98:101]
	v_mfma_f32_16x16x32_bf16 v[86:89], v[148:151], v[230:233], v[86:89]
	v_mfma_f32_16x16x32_bf16 v[82:85], v[156:159], v[230:233], v[82:85]
	v_mfma_f32_16x16x32_bf16 v[126:129], v[152:155], v[210:213], v[126:129]
	v_mfma_f32_16x16x32_bf16 v[122:125], v[160:163], v[210:213], v[122:125]
	v_mfma_f32_16x16x32_bf16 v[118:121], v[152:155], v[218:221], v[118:121]
	v_mfma_f32_16x16x32_bf16 v[114:117], v[160:163], v[218:221], v[114:117]
	v_mfma_f32_16x16x32_bf16 v[102:105], v[152:155], v[226:229], v[102:105]
	v_mfma_f32_16x16x32_bf16 v[98:101], v[160:163], v[226:229], v[98:101]
	v_mfma_f32_16x16x32_bf16 v[86:89], v[152:155], v[234:237], v[86:89]
	v_mfma_f32_16x16x32_bf16 v[82:85], v[160:163], v[234:237], v[82:85]
	v_mfma_f32_16x16x32_bf16 v[110:113], v[164:167], v[206:209], v[110:113]
	v_mfma_f32_16x16x32_bf16 v[106:109], v[198:201], v[206:209], v[106:109]
	v_mfma_f32_16x16x32_bf16 v[94:97], v[164:167], v[214:217], v[94:97]
	v_mfma_f32_16x16x32_bf16 v[90:93], v[198:201], v[214:217], v[90:93]
	v_mfma_f32_16x16x32_bf16 v[78:81], v[164:167], v[222:225], v[78:81]
	v_mfma_f32_16x16x32_bf16 v[74:77], v[198:201], v[222:225], v[74:77]
	v_mfma_f32_16x16x32_bf16 v[70:73], v[164:167], v[230:233], v[70:73]
	v_mfma_f32_16x16x32_bf16 v[66:69], v[198:201], v[230:233], v[66:69]
	v_mfma_f32_16x16x32_bf16 v[110:113], v[194:197], v[210:213], v[110:113]
	v_mfma_f32_16x16x32_bf16 v[106:109], v[202:205], v[210:213], v[106:109]
	v_mfma_f32_16x16x32_bf16 v[94:97], v[194:197], v[218:221], v[94:97]
	v_mfma_f32_16x16x32_bf16 v[90:93], v[202:205], v[218:221], v[90:93]
	v_mfma_f32_16x16x32_bf16 v[78:81], v[194:197], v[226:229], v[78:81]
	v_mfma_f32_16x16x32_bf16 v[74:77], v[202:205], v[226:229], v[74:77]
	v_mfma_f32_16x16x32_bf16 v[70:73], v[194:197], v[234:237], v[70:73]
	v_mfma_f32_16x16x32_bf16 v[66:69], v[202:205], v[234:237], v[66:69]
	s_barrier
	ds_read_b128 v[206:209], v147 offset:16384
	ds_read_b128 v[210:213], v147 offset:17408
	ds_read_b128 v[214:217], v147 offset:18432
	ds_read_b128 v[218:221], v147 offset:19456
	ds_read_b128 v[222:225], v147 offset:20480
	ds_read_b128 v[226:229], v147 offset:21504
	ds_read_b128 v[230:233], v147 offset:22528
	ds_read_b128 v[234:237], v147 offset:23552
	s_add_i32 s95, s95, s23
	v_lshl_add_u64 v[168:169], s[0:1], 0, v[32:33]
	s_mov_b32 m0, s95
	global_load_lds_dwordx4 v[168:169], off
	s_add_i32 m0, s95, 0x2000
	v_lshl_add_u64 v[238:239], s[0:1], 0, v[144:145]
	s_add_u32 s0, s0, s66
	s_addc_u32 s1, s1, s67
	s_add_i32 s95, s96, s23
	global_load_lds_dwordx4 v[238:239], off
	v_lshl_add_u64 v[240:241], s[0:1], 0, v[32:33]
	s_mov_b32 m0, s95
	v_lshl_add_u64 v[242:243], s[0:1], 0, v[144:145]
	global_load_lds_dwordx4 v[240:241], off
	s_add_i32 m0, s95, 0x2000
	v_lshl_add_u64 v[244:245], s[76:77], 0, v[140:141]
	global_load_lds_dwordx4 v[242:243], off
	s_mov_b32 m0, s53
	v_lshl_add_u64 v[246:247], s[76:77], 0, v[142:143]
	global_load_lds_dwordx4 v[244:245], off
	s_mov_b32 m0, s54
	s_nop 0
	global_load_lds_dwordx4 v[246:247], off
	s_waitcnt vmcnt(8)
	s_waitcnt lgkmcnt(0)
	s_barrier
	s_waitcnt lgkmcnt(0)
	v_mfma_f32_16x16x32_bf16 v[62:65], v[148:151], v[206:209], v[62:65]
	v_mfma_f32_16x16x32_bf16 v[58:61], v[156:159], v[206:209], v[58:61]
	v_mfma_f32_16x16x32_bf16 v[54:57], v[148:151], v[214:217], v[54:57]
	v_mfma_f32_16x16x32_bf16 v[50:53], v[156:159], v[214:217], v[50:53]
	v_mfma_f32_16x16x32_bf16 v[38:41], v[148:151], v[222:225], v[38:41]
	v_mfma_f32_16x16x32_bf16 v[34:37], v[156:159], v[222:225], v[34:37]
	v_mfma_f32_16x16x32_bf16 v[20:23], v[148:151], v[230:233], v[20:23]
	v_mfma_f32_16x16x32_bf16 v[16:19], v[156:159], v[230:233], v[16:19]
	v_mfma_f32_16x16x32_bf16 v[62:65], v[152:155], v[210:213], v[62:65]
	v_mfma_f32_16x16x32_bf16 v[58:61], v[160:163], v[210:213], v[58:61]
	v_mfma_f32_16x16x32_bf16 v[54:57], v[152:155], v[218:221], v[54:57]
	v_mfma_f32_16x16x32_bf16 v[50:53], v[160:163], v[218:221], v[50:53]
	v_mfma_f32_16x16x32_bf16 v[38:41], v[152:155], v[226:229], v[38:41]
	v_mfma_f32_16x16x32_bf16 v[34:37], v[160:163], v[226:229], v[34:37]
	v_mfma_f32_16x16x32_bf16 v[20:23], v[152:155], v[234:237], v[20:23]
	v_mfma_f32_16x16x32_bf16 v[16:19], v[160:163], v[234:237], v[16:19]
	v_mfma_f32_16x16x32_bf16 v[46:49], v[164:167], v[206:209], v[46:49]
	v_mfma_f32_16x16x32_bf16 v[42:45], v[198:201], v[206:209], v[42:45]
	v_mfma_f32_16x16x32_bf16 v[28:31], v[164:167], v[214:217], v[28:31]
	v_mfma_f32_16x16x32_bf16 v[24:27], v[198:201], v[214:217], v[24:27]
	v_mfma_f32_16x16x32_bf16 v[12:15], v[164:167], v[222:225], v[12:15]
	v_mfma_f32_16x16x32_bf16 v[8:11], v[198:201], v[222:225], v[8:11]
	v_mfma_f32_16x16x32_bf16 v[4:7], v[164:167], v[230:233], v[4:7]
	v_mfma_f32_16x16x32_bf16 v[0:3], v[198:201], v[230:233], v[0:3]
	v_mfma_f32_16x16x32_bf16 v[46:49], v[194:197], v[210:213], v[46:49]
	v_mfma_f32_16x16x32_bf16 v[42:45], v[202:205], v[210:213], v[42:45]
	v_mfma_f32_16x16x32_bf16 v[28:31], v[194:197], v[218:221], v[28:31]
	v_mfma_f32_16x16x32_bf16 v[24:27], v[202:205], v[218:221], v[24:27]
	v_mfma_f32_16x16x32_bf16 v[12:15], v[194:197], v[226:229], v[12:15]
	v_mfma_f32_16x16x32_bf16 v[8:11], v[202:205], v[226:229], v[8:11]
	v_mfma_f32_16x16x32_bf16 v[4:7], v[194:197], v[234:237], v[4:7]
	v_mfma_f32_16x16x32_bf16 v[0:3], v[202:205], v[234:237], v[0:3]
	s_barrier
	ds_read_b128 v[206:209], v147 offset:32768
	ds_read_b128 v[210:213], v147 offset:33792
	ds_read_b128 v[214:217], v147 offset:34816
	ds_read_b128 v[218:221], v147 offset:35840
	ds_read_b128 v[222:225], v147 offset:36864
	ds_read_b128 v[226:229], v147 offset:37888
	ds_read_b128 v[230:233], v147 offset:38912
	ds_read_b128 v[234:237], v147 offset:39936
	s_add_i32 s95, 0, 0x18000
	s_add_i32 s96, 0, 0x1c000
	v_add_u32_e32 v160, s95, v139
	v_add_u32_e32 v181, s96, v139
	ds_read_b128 v[148:151], v160
	ds_read_b128 v[152:155], v160 offset:1024
	ds_read_b128 v[156:159], v160 offset:2048
	ds_read_b128 v[160:163], v160 offset:3072
	ds_read_b128 v[164:167], v181
	ds_read_b128 v[194:197], v181 offset:1024
	ds_read_b128 v[198:201], v181 offset:2048
	ds_read_b128 v[202:205], v181 offset:3072
	s_add_u32 s0, s76, s66
	s_addc_u32 s1, s77, s67
	s_mov_b32 m0, s55
	v_lshl_add_u64 v[248:249], s[0:1], 0, v[140:141]
	global_load_lds_dwordx4 v[248:249], off
	v_lshl_add_u64 v[248:249], s[0:1], 0, v[142:143]
	s_mov_b32 m0, s56
	s_nop 0
	global_load_lds_dwordx4 v[248:249], off
	s_waitcnt vmcnt(8)
	s_waitcnt lgkmcnt(0)
	s_barrier
	s_waitcnt lgkmcnt(0)
	v_mfma_f32_16x16x32_bf16 v[126:129], v[148:151], v[206:209], v[126:129]
	v_mfma_f32_16x16x32_bf16 v[122:125], v[156:159], v[206:209], v[122:125]
	v_mfma_f32_16x16x32_bf16 v[118:121], v[148:151], v[214:217], v[118:121]
	v_mfma_f32_16x16x32_bf16 v[114:117], v[156:159], v[214:217], v[114:117]
	v_mfma_f32_16x16x32_bf16 v[102:105], v[148:151], v[222:225], v[102:105]
	v_mfma_f32_16x16x32_bf16 v[98:101], v[156:159], v[222:225], v[98:101]
	v_mfma_f32_16x16x32_bf16 v[86:89], v[148:151], v[230:233], v[86:89]
	v_mfma_f32_16x16x32_bf16 v[82:85], v[156:159], v[230:233], v[82:85]
	v_mfma_f32_16x16x32_bf16 v[126:129], v[152:155], v[210:213], v[126:129]
	v_mfma_f32_16x16x32_bf16 v[122:125], v[160:163], v[210:213], v[122:125]
	v_mfma_f32_16x16x32_bf16 v[118:121], v[152:155], v[218:221], v[118:121]
	v_mfma_f32_16x16x32_bf16 v[114:117], v[160:163], v[218:221], v[114:117]
	v_mfma_f32_16x16x32_bf16 v[102:105], v[152:155], v[226:229], v[102:105]
	v_mfma_f32_16x16x32_bf16 v[98:101], v[160:163], v[226:229], v[98:101]
	v_mfma_f32_16x16x32_bf16 v[86:89], v[152:155], v[234:237], v[86:89]
	v_mfma_f32_16x16x32_bf16 v[82:85], v[160:163], v[234:237], v[82:85]
	v_mfma_f32_16x16x32_bf16 v[110:113], v[164:167], v[206:209], v[110:113]
	v_mfma_f32_16x16x32_bf16 v[106:109], v[198:201], v[206:209], v[106:109]
	v_mfma_f32_16x16x32_bf16 v[94:97], v[164:167], v[214:217], v[94:97]
	v_mfma_f32_16x16x32_bf16 v[90:93], v[198:201], v[214:217], v[90:93]
	v_mfma_f32_16x16x32_bf16 v[78:81], v[164:167], v[222:225], v[78:81]
	v_mfma_f32_16x16x32_bf16 v[74:77], v[198:201], v[222:225], v[74:77]
	v_mfma_f32_16x16x32_bf16 v[70:73], v[164:167], v[230:233], v[70:73]
	v_mfma_f32_16x16x32_bf16 v[66:69], v[198:201], v[230:233], v[66:69]
	v_mfma_f32_16x16x32_bf16 v[110:113], v[194:197], v[210:213], v[110:113]
	v_mfma_f32_16x16x32_bf16 v[106:109], v[202:205], v[210:213], v[106:109]
	v_mfma_f32_16x16x32_bf16 v[94:97], v[194:197], v[218:221], v[94:97]
	v_mfma_f32_16x16x32_bf16 v[90:93], v[202:205], v[218:221], v[90:93]
	v_mfma_f32_16x16x32_bf16 v[78:81], v[194:197], v[226:229], v[78:81]
	v_mfma_f32_16x16x32_bf16 v[74:77], v[202:205], v[226:229], v[74:77]
	v_mfma_f32_16x16x32_bf16 v[70:73], v[194:197], v[234:237], v[70:73]
	v_mfma_f32_16x16x32_bf16 v[66:69], v[202:205], v[234:237], v[66:69]
	s_barrier
	ds_read_b128 v[206:209], v147 offset:49152
	ds_read_b128 v[210:213], v147 offset:50176
	ds_read_b128 v[214:217], v147 offset:51200
	ds_read_b128 v[218:221], v147 offset:52224
	ds_read_b128 v[222:225], v147 offset:53248
	ds_read_b128 v[226:229], v147 offset:54272
	ds_read_b128 v[230:233], v147 offset:55296
	ds_read_b128 v[234:237], v147 offset:56320
	s_add_i32 s0, s95, s23
	v_lshl_add_u64 v[168:169], v[168:169], 0, s[26:27]
	s_mov_b32 m0, s0
	global_load_lds_dwordx4 v[168:169], off
	v_lshl_add_u64 v[168:169], v[238:239], 0, s[26:27]
	s_add_i32 m0, s0, 0x2000
	s_add_i32 s0, s96, s23
	global_load_lds_dwordx4 v[168:169], off
	v_lshl_add_u64 v[168:169], v[240:241], 0, s[26:27]
	s_mov_b32 m0, s0
	s_nop 0
	global_load_lds_dwordx4 v[168:169], off
	v_lshl_add_u64 v[168:169], v[242:243], 0, s[26:27]
	s_add_i32 m0, s0, 0x2000
	s_nop 0
	global_load_lds_dwordx4 v[168:169], off
	v_lshl_add_u64 v[168:169], v[244:245], 0, s[26:27]
	s_mov_b32 m0, s57
	s_nop 0
	global_load_lds_dwordx4 v[168:169], off
	v_lshl_add_u64 v[168:169], v[246:247], 0, s[26:27]
	s_mov_b32 m0, s78
	s_nop 0
	global_load_lds_dwordx4 v[168:169], off
	s_waitcnt vmcnt(8)
	s_waitcnt lgkmcnt(0)
	s_barrier
	s_waitcnt lgkmcnt(0)
	v_mfma_f32_16x16x32_bf16 v[62:65], v[148:151], v[206:209], v[62:65]
	v_mfma_f32_16x16x32_bf16 v[58:61], v[156:159], v[206:209], v[58:61]
	v_mfma_f32_16x16x32_bf16 v[54:57], v[148:151], v[214:217], v[54:57]
	v_mfma_f32_16x16x32_bf16 v[50:53], v[156:159], v[214:217], v[50:53]
	v_mfma_f32_16x16x32_bf16 v[38:41], v[148:151], v[222:225], v[38:41]
	v_mfma_f32_16x16x32_bf16 v[34:37], v[156:159], v[222:225], v[34:37]
	v_mfma_f32_16x16x32_bf16 v[20:23], v[148:151], v[230:233], v[20:23]
	v_mfma_f32_16x16x32_bf16 v[16:19], v[156:159], v[230:233], v[16:19]
	v_mfma_f32_16x16x32_bf16 v[62:65], v[152:155], v[210:213], v[62:65]
	v_mfma_f32_16x16x32_bf16 v[58:61], v[160:163], v[210:213], v[58:61]
	v_mfma_f32_16x16x32_bf16 v[54:57], v[152:155], v[218:221], v[54:57]
	v_mfma_f32_16x16x32_bf16 v[50:53], v[160:163], v[218:221], v[50:53]
	v_mfma_f32_16x16x32_bf16 v[38:41], v[152:155], v[226:229], v[38:41]
	v_mfma_f32_16x16x32_bf16 v[34:37], v[160:163], v[226:229], v[34:37]
	v_mfma_f32_16x16x32_bf16 v[20:23], v[152:155], v[234:237], v[20:23]
	v_mfma_f32_16x16x32_bf16 v[16:19], v[160:163], v[234:237], v[16:19]
	v_mfma_f32_16x16x32_bf16 v[46:49], v[164:167], v[206:209], v[46:49]
	v_mfma_f32_16x16x32_bf16 v[42:45], v[198:201], v[206:209], v[42:45]
	v_mfma_f32_16x16x32_bf16 v[28:31], v[164:167], v[214:217], v[28:31]
	v_mfma_f32_16x16x32_bf16 v[24:27], v[198:201], v[214:217], v[24:27]
	v_mfma_f32_16x16x32_bf16 v[12:15], v[164:167], v[222:225], v[12:15]
	v_mfma_f32_16x16x32_bf16 v[8:11], v[198:201], v[222:225], v[8:11]
	v_mfma_f32_16x16x32_bf16 v[4:7], v[164:167], v[230:233], v[4:7]
	v_mfma_f32_16x16x32_bf16 v[0:3], v[198:201], v[230:233], v[0:3]
	v_mfma_f32_16x16x32_bf16 v[46:49], v[194:197], v[210:213], v[46:49]
	v_mfma_f32_16x16x32_bf16 v[42:45], v[202:205], v[210:213], v[42:45]
	v_mfma_f32_16x16x32_bf16 v[28:31], v[194:197], v[218:221], v[28:31]
	v_mfma_f32_16x16x32_bf16 v[24:27], v[202:205], v[218:221], v[24:27]
	v_mfma_f32_16x16x32_bf16 v[12:15], v[194:197], v[226:229], v[12:15]
	v_mfma_f32_16x16x32_bf16 v[8:11], v[202:205], v[226:229], v[8:11]
	v_mfma_f32_16x16x32_bf16 v[4:7], v[194:197], v[234:237], v[4:7]
	v_mfma_f32_16x16x32_bf16 v[0:3], v[202:205], v[234:237], v[0:3]
	s_add_u32 s74, s74, 0x100
	s_addc_u32 s75, s75, 0
	s_add_u32 s85, s85, 0x100
	s_addc_u32 s90, s90, 0
	s_cmp_ge_i32 s91, s94
	s_mov_b32 s76, s91
	s_barrier
	s_cbranch_scc0 .LBB0_356
	s_and_b64 vcc, exec, s[72:73]
	s_cbranch_vccz .LBB0_359
	s_barrier
